# P1/P8 epilogues rewritten (32-bit saddr stores, packed f32 SwiGLU math, same op order per element) and P9 tile-wave order reversed for MALL reuse of the P8 output
# speedup vs baseline: 1.0239x; 1.0015x over previous
.LBB0_9:
	s_add_u32 s50, s4, 0x200000
	s_addc_u32 s51, s5, 0
	s_add_u32 s60, s6, 0x1e00000
	s_addc_u32 s61, s7, 0
	s_add_u32 s62, s8, 0x2600000
	s_addc_u32 s63, s9, 0
	s_add_u32 s64, s10, 0x5200000
	s_addc_u32 s65, s11, 0
	s_add_u32 s66, s12, 0x6800000
	s_addc_u32 s67, s13, 0
	s_add_u32 s68, s14, 0xe800000
	s_addc_u32 s69, s15, 0
	s_cmp_lt_i32 s58, 1
	s_cselect_b64 s[4:5], -1, 0
	s_cmp_gt_i32 s59, 0
	s_cselect_b64 s[6:7], -1, 0
	s_and_b64 s[70:71], s[4:5], s[6:7]
	s_lshl_b32 s4, s0, 14
	v_readlane_b32 s29, v250, 0
	s_add_i32 s72, s4, 0
	s_lshl_b32 s4, s29, 3
	s_add_i32 s23, s4, s0
	s_lshl_b32 s78, s46, 3
	s_cmpk_lt_i32 s23, 0x6600
	s_cselect_b64 s[4:5], -1, 0
	v_writelane_b32 v250, s4, 1
	s_cmpk_lt_i32 s23, 0x230
	s_mul_hi_i32 s20, s42, 0x2aaaaaab
	v_writelane_b32 v250, s5, 2
	s_cselect_b64 s[4:5], -1, 0
	v_writelane_b32 v250, s4, 3
	s_lshl_b32 s12, s0, 2
	s_mov_b32 s39, 0
	v_writelane_b32 v250, s5, 4
	s_lshl_b32 s4, s29, 5
	s_add_i32 s30, s4, s12
	s_cmp_lt_i32 s30, 0x8000
	v_writelane_b32 v250, s4, 5
	s_cselect_b64 s[4:5], -1, 0
	v_writelane_b32 v250, s4, 6
	s_lshl_b32 s34, s46, 5
	v_mov_b32_e32 v153, 0
	v_writelane_b32 v250, s5, 7
	s_sub_i32 s4, 0, s47
	v_writelane_b32 v250, s4, 8
	s_add_u32 s4, s54, 0x4200
	s_addc_u32 s5, s55, 0
	v_writelane_b32 v250, s4, 9
	v_mov_b32_e32 v206, 0x358637bd
	v_mov_b32_e32 v207, 0x260
	v_writelane_b32 v250, s5, 10
	s_add_u32 s4, s54, 0x4400
	s_addc_u32 s5, s55, 0
	v_writelane_b32 v250, s4, 11
	v_mov_b32_e32 v208, 1
	v_mov_b32_e32 v209, 0x3fa00000
	v_writelane_b32 v250, s5, 12
	s_add_u32 s4, s54, 0x4500
	s_addc_u32 s5, s55, 0
	v_writelane_b32 v250, s4, 13
	v_mov_b32_e32 v154, 1.0
	v_mov_b32_e32 v210, 0x3800
	v_writelane_b32 v250, s5, 14
	s_add_u32 s4, s54, 0x4600
	s_addc_u32 s5, s55, 0
	v_writelane_b32 v250, s4, 15
	v_mov_b32_e32 v211, 0x9f
	v_mov_b32_e32 v212, 0xff61b1e6
	v_writelane_b32 v250, s5, 16
	s_add_u32 s4, s54, 0x4700
	s_addc_u32 s5, s55, 0
	v_writelane_b32 v250, s4, 17
	v_mov_b32_e32 v213, 0x80
	v_mov_b64_e32 v[156:157], 0x400
	v_writelane_b32 v250, s5, 18
	s_add_u32 s4, s54, 0x4800
	s_addc_u32 s5, s55, 0
	v_writelane_b32 v250, s4, 19
	v_mov_b64_e32 v[158:159], 0x3ff
	v_mov_b64_e32 v[160:161], 0x15ff
	v_writelane_b32 v250, s5, 20
	s_add_u32 s4, s54, 0x4900
	s_addc_u32 s5, s55, 0
	v_writelane_b32 v250, s4, 21
	s_nop 1
	v_writelane_b32 v250, s5, 22
	s_add_u32 s4, s54, 0x4a00
	s_addc_u32 s5, s55, 0
	v_writelane_b32 v250, s4, 23
	s_nop 1
	v_writelane_b32 v250, s5, 24
	s_add_u32 s4, s54, 0x4b00
	s_addc_u32 s5, s55, 0
	v_writelane_b32 v250, s4, 25
	s_nop 1
	v_writelane_b32 v250, s5, 26
	s_add_u32 s4, s54, 0x4c00
	s_addc_u32 s5, s55, 0
	v_writelane_b32 v250, s4, 27
	s_nop 1
	v_writelane_b32 v250, s5, 28
	s_add_u32 s4, s54, 0x4d00
	s_addc_u32 s5, s55, 0
	v_writelane_b32 v250, s4, 29
	s_nop 1
	v_writelane_b32 v250, s5, 30
	s_add_u32 s4, s54, 0x4e00
	s_addc_u32 s5, s55, 0
	v_writelane_b32 v250, s4, 31
	s_nop 1
	v_writelane_b32 v250, s5, 32
	s_add_u32 s4, s54, 0x4f00
	s_addc_u32 s5, s55, 0
	v_writelane_b32 v250, s4, 33
	s_nop 1
	v_writelane_b32 v250, s5, 34
	s_add_u32 s4, s54, 0x5000
	s_addc_u32 s5, s55, 0
	v_writelane_b32 v250, s4, 35
	s_nop 1
	v_writelane_b32 v250, s5, 36
	s_add_u32 s4, s54, 0x5100
	s_addc_u32 s5, s55, 0
	v_writelane_b32 v250, s4, 37
	s_nop 1
	v_writelane_b32 v250, s5, 38
	s_add_u32 s4, s54, 0x5200
	s_addc_u32 s5, s55, 0
	v_writelane_b32 v250, s4, 39
	s_nop 1
	v_writelane_b32 v250, s5, 40
	s_add_u32 s4, s54, 0x5300
	s_addc_u32 s5, s55, 0
	v_writelane_b32 v250, s4, 41
	s_cmp_eq_u32 s1, 15
	s_nop 0
	v_writelane_b32 v250, s5, 42
	s_cselect_b64 s[4:5], -1, 0
	v_writelane_b32 v250, s4, 43
	s_cmp_eq_u32 s1, 14
	s_nop 0
	v_writelane_b32 v250, s5, 44
	s_cselect_b64 s[4:5], -1, 0
	v_writelane_b32 v250, s4, 45
	s_cmp_eq_u32 s1, 13
	s_nop 0
	v_writelane_b32 v250, s5, 46
	s_cselect_b64 s[4:5], -1, 0
	v_writelane_b32 v250, s4, 47
	s_cmp_eq_u32 s1, 12
	s_nop 0
	v_writelane_b32 v250, s5, 48
	s_cselect_b64 s[4:5], -1, 0
	v_writelane_b32 v250, s4, 49
	s_cmp_eq_u32 s1, 11
	s_nop 0
	v_writelane_b32 v250, s5, 50
	s_cselect_b64 s[4:5], -1, 0
	v_writelane_b32 v250, s4, 51
	s_cmp_eq_u32 s1, 10
	s_nop 0
	v_writelane_b32 v250, s5, 52
	s_cselect_b64 s[4:5], -1, 0
	v_writelane_b32 v250, s4, 53
	s_cmp_eq_u32 s1, 9
	s_nop 0
	v_writelane_b32 v250, s5, 54
	s_cselect_b64 s[4:5], -1, 0
	v_writelane_b32 v250, s4, 55
	s_cmp_eq_u32 s1, 8
	s_nop 0
	v_writelane_b32 v250, s5, 56
	s_cselect_b64 s[4:5], -1, 0
	v_writelane_b32 v250, s4, 57
	s_cmp_eq_u32 s1, 7
	s_nop 0
	v_writelane_b32 v250, s5, 58
	s_cselect_b64 s[4:5], -1, 0
	v_writelane_b32 v250, s4, 59
	s_cmp_eq_u32 s1, 6
	s_nop 0
	v_writelane_b32 v250, s5, 60
	s_cselect_b64 s[4:5], -1, 0
	v_writelane_b32 v250, s4, 61
	s_cmp_eq_u32 s1, 5
	s_nop 0
	v_writelane_b32 v250, s5, 62
	s_cselect_b64 s[4:5], -1, 0
	v_writelane_b32 v250, s4, 63
	s_cmp_eq_u32 s1, 4
	s_nop 0
	v_writelane_b32 v252, s5, 0
	s_cselect_b64 s[4:5], -1, 0
	v_writelane_b32 v252, s4, 1
	s_cmp_eq_u32 s1, 3
	s_nop 0
	v_writelane_b32 v252, s5, 2
	s_cselect_b64 s[4:5], -1, 0
	v_writelane_b32 v252, s4, 3
	s_cmp_eq_u32 s1, 2
	s_nop 0
	v_writelane_b32 v252, s5, 4
	s_cselect_b64 s[4:5], -1, 0
	v_writelane_b32 v252, s4, 5
	s_cmp_eq_u32 s1, 1
	s_nop 0
	v_writelane_b32 v252, s5, 6
	s_cselect_b64 s[4:5], -1, 0
	v_writelane_b32 v252, s4, 7
	s_cmp_eq_u32 s1, 0
	s_nop 0
	v_writelane_b32 v252, s5, 8
	s_cselect_b64 s[4:5], -1, 0
	s_lshl_b32 s1, s1, 8
	s_add_u32 s1, s2, s1
	v_writelane_b32 v252, s4, 9
	s_addc_u32 s2, s3, 0
	s_nop 0
	v_writelane_b32 v252, s5, 10
	s_add_u32 s4, s1, 0x1400
	s_addc_u32 s5, s2, 0
	v_writelane_b32 v252, s4, 11
	s_nop 1
	v_writelane_b32 v252, s5, 12
	s_add_u32 s4, s1, 0x2400
	s_addc_u32 s5, s2, 0
	v_writelane_b32 v252, s4, 13
	s_add_u32 s2, s54, 0x7400
	s_addc_u32 s3, s55, 0
	v_writelane_b32 v252, s5, 14
	v_writelane_b32 v252, s2, 15
	s_nop 1
	v_writelane_b32 v252, s3, 16
	s_add_u32 s2, s54, 0x7500
	s_addc_u32 s3, s55, 0
	v_writelane_b32 v252, s2, 17
	s_cmp_lt_i32 s58, 2
	s_nop 0
	v_writelane_b32 v252, s3, 18
	s_cselect_b64 s[2:3], -1, 0
	s_cmp_gt_i32 s59, 1
	s_cselect_b64 s[4:5], -1, 0
	s_and_b64 s[2:3], s[2:3], s[4:5]
	v_writelane_b32 v252, s2, 19
	s_cmpk_lt_i32 s42, 0xe00
	s_nop 0
	v_writelane_b32 v252, s3, 20
	s_cselect_b64 s[2:3], -1, 0
	s_ashr_i32 s43, s42, 31
	s_lshr_b32 s1, s43, 29
	s_add_i32 s1, s42, s1
	s_ashr_i32 s21, s1, 3
	s_and_b32 s1, s1, -8
	s_sub_i32 s22, s42, s1
	s_ashr_i32 s1, s46, 31
	v_writelane_b32 v252, s2, 21
	s_cmp_lt_i32 s58, 3
	s_nop 0
	v_writelane_b32 v252, s3, 22
	s_cselect_b64 s[2:3], -1, 0
	s_cmp_gt_i32 s59, 2
	s_cselect_b64 s[4:5], -1, 0
	v_writelane_b32 v252, s1, 23
	s_and_b64 s[2:3], s[2:3], s[4:5]
	v_writelane_b32 v252, s2, 24
	s_cmpk_lt_i32 s23, 0x6000
	s_nop 0
	v_writelane_b32 v252, s3, 25
	s_cselect_b64 s[2:3], -1, 0
	v_writelane_b32 v252, s2, 26
	s_cmpk_lt_i32 s29, 0x100
	s_nop 0
	v_writelane_b32 v252, s3, 27
	s_cselect_b64 s[2:3], -1, 0
	v_writelane_b32 v252, s2, 28
	s_cmp_lg_u32 s0, 0
	s_nop 0
	v_writelane_b32 v252, s3, 29
	s_cselect_b64 s[2:3], -1, 0
	v_writelane_b32 v252, s2, 30
	s_cmp_lt_i32 s58, 4
	s_nop 0
	v_writelane_b32 v252, s3, 31
	s_cselect_b64 s[2:3], -1, 0
	s_cmp_gt_i32 s59, 3
	s_cselect_b64 s[4:5], -1, 0
	s_and_b64 s[2:3], s[2:3], s[4:5]
	v_writelane_b32 v252, s2, 32
	s_cmpk_lt_i32 s23, 0xc00
	s_nop 0
	v_writelane_b32 v252, s3, 33
	s_cselect_b64 s[2:3], -1, 0
	s_lshl_b32 s1, s0, 10
	v_writelane_b32 v252, s2, 34
	s_add_i32 s1, s1, 0
	s_add_i32 s1, s1, 0x22000
	v_writelane_b32 v252, s3, 35
	v_writelane_b32 v252, s1, 36
	s_sub_i32 s1, 0xc00, s78
	s_cmpk_gt_i32 s46, 0x17f
	s_cselect_b64 s[2:3], -1, 0
	s_cmp_le_i32 s78, s1
	s_cselect_b64 s[4:5], -1, 0
	s_or_b64 s[2:3], s[2:3], s[4:5]
	v_writelane_b32 v252, s2, 37
	s_cmpk_lt_i32 s23, 0x1000
	s_nop 0
	v_writelane_b32 v252, s3, 38
	s_cselect_b64 s[2:3], -1, 0
	v_writelane_b32 v252, s2, 39
	s_cmp_ge_i32 s23, s1
	s_nop 0
	v_writelane_b32 v252, s3, 40
	s_cselect_b64 s[2:3], -1, 0
	v_writelane_b32 v252, s2, 41
	s_sub_i32 s33, s78, s1
	s_nop 0
	v_writelane_b32 v252, s3, 42
	s_sub_i32 s2, s23, s1
	s_cmpk_lt_i32 s2, 0x1000
	v_writelane_b32 v252, s2, 43
	s_cselect_b64 s[2:3], -1, 0
	v_writelane_b32 v252, s2, 44
	s_cmpk_lt_i32 s23, 0x800
	s_nop 0
	v_writelane_b32 v252, s3, 45
	s_cselect_b64 s[2:3], -1, 0
	v_writelane_b32 v252, s2, 46
	s_cmp_lt_i32 s58, 5
	s_nop 0
	v_writelane_b32 v252, s3, 47
	s_cselect_b64 s[2:3], -1, 0
	s_cmp_gt_i32 s59, 4
	s_cselect_b64 s[4:5], -1, 0
	s_and_b64 s[2:3], s[2:3], s[4:5]
	v_writelane_b32 v252, s2, 48
	s_cmp_lt_i32 s0, 4
	s_nop 0
	v_writelane_b32 v252, s3, 49
	s_cselect_b64 s[2:3], -1, 0
	s_lshr_b32 s1, s20, 31
	s_add_i32 s20, s20, s1
	s_mul_i32 s1, s20, 6
	v_writelane_b32 v252, s2, 50
	s_sub_i32 s1, s42, s1
	s_lshl_b32 s4, s0, 5
	v_writelane_b32 v252, s3, 51
	s_lshl_b32 s2, s1, 7
	s_add_i32 s1, s0, -4
	s_lshl_b32 s14, s0, 11
	s_lshl_b32 s16, s42, 5
	s_lshl_b32 s36, s1, 11
	s_lshl_b32 s38, s1, 10
	s_ashr_i32 s3, s2, 31
	s_ashr_i32 s5, s4, 31
	s_ashr_i32 s15, s14, 31
	s_ashr_i32 s17, s16, 31
	s_ashr_i32 s37, s36, 31
	s_lshl_b32 s6, s1, 12
	s_lshl_b64 s[40:41], s[42:43], 19
	s_lshl_b64 s[10:11], s[42:43], 18
	s_ashr_i32 s13, s38, 31
	v_writelane_b32 v252, s6, 52
	s_add_u32 s1, s54, 0x10000
	v_writelane_b32 v252, s1, 53
	s_addc_u32 s1, s55, 0
	v_writelane_b32 v252, s1, 54
	s_sub_i32 s1, 0xff, s42
	s_add_i32 s8, s42, 0xffffffa0
	s_cmpk_lt_i32 s42, 0x60
	s_cselect_b64 s[6:7], -1, 0
	v_writelane_b32 v252, s6, 55
	s_nop 1
	v_writelane_b32 v252, s7, 56
	s_and_b64 s[6:7], s[6:7], exec
	s_cselect_b32 s1, s1, s8
	s_cmpk_lt_i32 s42, 0x100
	v_writelane_b32 v252, s1, 57
	s_cselect_b64 s[6:7], -1, 0
	s_lshl_b32 s1, s0, 13
	s_add_i32 s9, s1, 0
	s_mul_i32 s8, s0, 0xffffe400
	v_writelane_b32 v252, s9, 58
	s_add_i32 s8, s9, s8
	s_ashr_i32 s1, s0, 31
	v_writelane_b32 v252, s8, 59
	s_lshl_b32 s18, s0, 9
	s_add_i32 s8, s4, 0x700
	s_ashr_i32 s19, s18, 31
	v_writelane_b32 v252, s8, 60
	s_lshl_b64 s[8:9], s[0:1], 9
	s_cmp_lt_i32 s58, 6
	s_cselect_b64 s[24:25], -1, 0
	s_cmp_gt_i32 s59, 5
	s_cselect_b64 s[26:27], -1, 0
	s_and_b64 s[24:25], s[24:25], s[26:27]
	v_writelane_b32 v252, s24, 61
	s_cmpk_lt_i32 s23, 0x3000
	s_nop 0
	v_writelane_b32 v252, s25, 62
	s_cselect_b64 s[24:25], -1, 0
	v_writelane_b32 v252, s24, 63
	s_cmp_lt_i32 s58, 7
	s_nop 0
	v_writelane_b32 v253, s25, 0
	s_cselect_b64 s[24:25], -1, 0
	s_cmp_gt_i32 s59, 6
	s_cselect_b64 s[26:27], -1, 0
	s_and_b64 s[24:25], s[24:25], s[26:27]
	v_writelane_b32 v253, s24, 1
	s_cmpk_lt_i32 s42, 0x400
	s_nop 0
	v_writelane_b32 v253, s25, 2
	s_cselect_b64 s[24:25], -1, 0
	s_lshl_b32 s1, s22, 7
	v_writelane_b32 v253, s24, 3
	s_cmp_lt_i32 s58, 8
	s_nop 0
	v_writelane_b32 v253, s25, 4
	s_cselect_b64 s[24:25], -1, 0
	s_cmp_gt_i32 s59, 7
	s_cselect_b64 s[26:27], -1, 0
	s_and_b64 s[24:25], s[24:25], s[26:27]
	v_writelane_b32 v253, s24, 5
	s_cmp_lt_i32 s58, 9
	s_nop 0
	v_writelane_b32 v253, s25, 6
	s_cselect_b64 s[24:25], -1, 0
	s_cmp_gt_i32 s59, 8
	s_cselect_b64 s[26:27], -1, 0
	s_and_b64 s[24:25], s[24:25], s[26:27]
	v_writelane_b32 v253, s24, 7
	s_cmpk_lt_i32 s42, 0x1600
	s_nop 0
	v_writelane_b32 v253, s25, 8
	s_cselect_b64 s[24:25], -1, 0
	v_writelane_b32 v253, s24, 9
	s_cmp_gt_i32 s58, 9
	s_mov_b32 s58, s23
	v_writelane_b32 v253, s25, 10
	s_cselect_b64 s[24:25], -1, 0
	s_cmp_lt_i32 s59, 10
	s_cselect_b64 s[26:27], -1, 0
	s_or_b64 s[24:25], s[24:25], s[26:27]
	s_cmp_lt_i32 s22, 0
	s_mul_i32 s23, s22, 0x81
	s_cselect_b32 s1, s23, s1
	s_movk_i32 s23, 0x1c1
	v_writelane_b32 v253, s24, 11
	s_cselect_b32 s23, s23, 0x1c0
	s_mul_i32 s23, s22, s23
	v_writelane_b32 v253, s25, 12
	s_movk_i32 s24, 0x2c1
	s_cselect_b32 s28, s24, 0x2c0
	s_add_i32 s23, s23, s21
	s_mul_hi_i32 s24, s23, 0x92492493
	s_add_i32 s24, s24, s23
	s_lshr_b32 s25, s24, 31
	s_ashr_i32 s24, s24, 6
	s_add_i32 s24, s24, s25
	s_mul_i32 s25, s24, 0x70
	s_sub_i32 s23, s23, s25
	s_bfe_i32 s25, s23, 0x80000
	s_bfe_u32 s25, s25, 0x2000d
	s_add_i32 s25, s23, s25
	s_and_b32 s26, s25, 0xfc
	s_sub_i32 s23, s23, s26
	s_bfe_i32 s25, s25, 0x80000
	s_lshl_b32 s24, s24, 2
	s_sext_i32_i16 s25, s25
	s_sext_i32_i8 s23, s23
	s_add_i32 s74, s24, s23
	s_ashr_i32 s23, s25, 2
	v_writelane_b32 v253, s23, 13
	s_lshr_b32 s24, s25, 2
	s_mov_b32 s26, s74
	s_ashr_i32 s75, s74, 31
	s_bfe_i64 s[24:25], s[24:25], 0x100000
	v_writelane_b32 v253, s26, 14
	s_lshl_b64 s[24:25], s[24:25], 20
	s_nop 0
	v_writelane_b32 v253, s27, 15
	s_lshl_b64 s[26:27], s[74:75], 20
	s_add_u32 s24, s50, s24
	s_addc_u32 s25, s51, s25
	s_add_u32 s74, s24, 0x80000
	s_addc_u32 s75, s25, 0
	v_writelane_b32 v253, s74, 16
	s_add_u32 s26, s66, s26
	s_addc_u32 s27, s67, s27
	v_writelane_b32 v253, s75, 17
	s_add_u32 s74, s26, 0x80000
	v_writelane_b32 v253, s26, 18
	s_addc_u32 s75, s27, 0
	s_nop 0
	v_writelane_b32 v253, s27, 19
	v_writelane_b32 v253, s74, 20
	s_add_u32 s26, s24, 0x80080
	s_nop 0
	v_writelane_b32 v253, s75, 21
	v_writelane_b32 v253, s24, 22
	s_addc_u32 s27, s25, 0
	s_add_i32 s1, s1, s21
	s_ashr_i32 s23, s1, 31
	s_lshr_b32 s23, s23, 27
	s_add_i32 s23, s1, s23
	v_writelane_b32 v253, s25, 23
	s_and_b32 s24, s23, 0xffe0
	s_sub_i32 s1, s1, s24
	s_bfe_i32 s24, s1, 0x80000
	s_bfe_u32 s24, s24, 0x2000d
	s_add_i32 s24, s1, s24
	s_and_b32 s25, s24, 0xfc
	s_sub_i32 s1, s1, s25
	s_ashr_i32 s23, s23, 5
	s_bfe_i32 s24, s24, 0x80000
	s_lshl_b32 s23, s23, 2
	s_sext_i32_i16 s24, s24
	s_sext_i32_i8 s1, s1
	s_add_i32 s74, s23, s1
	s_ashr_i32 s31, s24, 2
	s_lshr_b32 s24, s24, 2
	v_writelane_b32 v253, s26, 24
	s_ashr_i32 s75, s74, 31
	s_bfe_i64 s[24:25], s[24:25], 0x100000
	v_writelane_b32 v253, s27, 25
	s_lshl_b64 s[24:25], s[24:25], 20
	s_lshl_b64 s[26:27], s[74:75], 20
	s_add_u32 s24, s60, s24
	s_addc_u32 s25, s61, s25
	s_add_u32 s76, s24, 0x80000
	s_addc_u32 s77, s25, 0
	v_writelane_b32 v253, s76, 26
	s_add_u32 s26, s66, s26
	s_addc_u32 s27, s67, s27
	v_writelane_b32 v253, s77, 27
	s_mul_i32 s1, s22, s28
	s_add_u32 s22, s26, 0x80000
	v_writelane_b32 v253, s26, 28
	s_addc_u32 s23, s27, 0
	s_nop 0
	v_writelane_b32 v253, s27, 29
	v_writelane_b32 v253, s22, 30
	s_nop 1
	v_writelane_b32 v253, s23, 31
	s_add_u32 s22, s24, 0x80080
	v_writelane_b32 v253, s24, 32
	s_addc_u32 s23, s25, 0
	s_add_i32 s1, s1, s21
	v_writelane_b32 v253, s25, 33
	v_writelane_b32 v253, s22, 34
	s_mul_hi_i32 s21, s1, 0x2e8ba2e9
	s_nop 0
	v_writelane_b32 v253, s23, 35
	s_lshr_b32 s22, s21, 31
	s_ashr_i32 s21, s21, 5
	s_add_i32 s21, s21, s22
	s_mul_i32 s22, s21, 0xb0
	s_sub_i32 s1, s1, s22
	s_bfe_u32 s22, s1, 0x2001d
	s_add_i32 s22, s1, s22
	s_and_b32 s23, s22, 0xfffc
	s_sub_i32 s1, s1, s23
	s_lshl_b32 s21, s21, 2
	s_sext_i32_i16 s22, s22
	s_sext_i32_i16 s1, s1
	s_add_i32 s26, s21, s1
	s_ashr_i32 s1, s22, 2
	v_writelane_b32 v253, s1, 36
	s_lshr_b32 s22, s22, 2
	s_mov_b32 s24, s26
	s_ashr_i32 s27, s26, 31
	s_bfe_i64 s[22:23], s[22:23], 0x100000
	v_writelane_b32 v253, s24, 37
	s_lshl_b64 s[22:23], s[22:23], 20
	s_mul_i32 s21, s31, 0x2c0000
	v_writelane_b32 v253, s25, 38
	s_lshl_b64 s[24:25], s[26:27], 20
	s_add_u32 s22, s62, s22
	s_addc_u32 s23, s63, s23
	s_add_u32 s26, s22, 0x80000
	s_addc_u32 s27, s23, 0
	v_writelane_b32 v253, s26, 39
	s_add_u32 s24, s66, s24
	s_addc_u32 s25, s67, s25
	v_writelane_b32 v253, s27, 40
	s_add_u32 s26, s24, 0x80000
	v_writelane_b32 v253, s24, 41
	s_addc_u32 s27, s25, 0
	s_mul_hi_i32 s1, s31, 0x2c0000
	v_writelane_b32 v253, s25, 42
	v_writelane_b32 v253, s26, 43
	s_add_u32 s24, s22, 0x80080
	s_nop 0
	v_writelane_b32 v253, s27, 44
	v_writelane_b32 v253, s22, 45
	s_addc_u32 s25, s23, 0
	s_nop 0
	v_writelane_b32 v253, s23, 46
	v_writelane_b32 v253, s24, 47
	s_nop 1
	v_writelane_b32 v253, s25, 48
	s_add_u32 s24, s64, s21
	s_addc_u32 s25, s65, s1
	s_add_u32 s22, s24, 0x160000
	v_writelane_b32 v253, s31, 49
	s_addc_u32 s23, s25, 0
	v_writelane_b32 v253, s22, 50
	s_xor_b32 s74, s74, 12
	s_mul_i32 s21, s74, 0x2c0000
	s_mul_hi_i32 s1, s74, 0x2c0000
	s_xor_b32 s74, s74, 12
	v_writelane_b32 v253, s23, 51
	s_mov_b32 s22, s74
	v_writelane_b32 v253, s22, 52
	s_nop 1
	v_writelane_b32 v253, s23, 53
	s_add_u32 s22, s68, s21
	s_addc_u32 s23, s69, s1
	s_add_u32 s26, s22, 0x160000
	v_writelane_b32 v253, s22, 54
	s_addc_u32 s27, s23, 0
	s_nop 0
	v_writelane_b32 v253, s23, 55
	v_writelane_b32 v253, s26, 56
	s_add_u32 s22, s24, 0x160080
	s_nop 0
	v_writelane_b32 v253, s27, 57
	v_writelane_b32 v253, s24, 58
	s_addc_u32 s23, s25, 0
	s_lshl_b32 s1, s29, 11
	v_writelane_b32 v253, s25, 59
	v_writelane_b32 v253, s22, 60
	s_lshl_b32 s21, s0, 8
	s_add_i32 s1, s1, s21
	v_writelane_b32 v253, s23, 61
	v_writelane_b32 v253, s1, 62
	s_lshl_b32 s1, s56, 1
	s_ashr_i32 s31, s30, 31
	v_writelane_b32 v253, s1, 63
	s_add_i32 s1, s58, 0xfffffdf0
	v_writelane_b32 v254, s1, 0
	s_lshl_b32 s1, s46, 11
	s_lshl_b64 s[22:23], s[30:31], 12
	v_writelane_b32 v254, s1, 1
	s_add_u32 s1, s22, 0x6803e00
	v_writelane_b32 v254, s1, 2
	s_addc_u32 s1, s23, 0
	v_writelane_b32 v254, s1, 3
	s_mov_b32 s22, s30
	v_writelane_b32 v254, s22, 4
	s_lshl_b64 s[18:19], s[18:19], 1
	s_ashr_i32 s35, s34, 31
	v_writelane_b32 v254, s23, 5
	s_lshl_b64 s[22:23], s[30:31], 13
	v_writelane_b32 v254, s18, 6
	s_mul_i32 s0, s0, 0xe000
	s_or_b32 s22, s22, 0x7c00
	v_writelane_b32 v254, s19, 7
	s_lshl_b64 s[18:19], s[34:35], 12
	s_lshl_b64 s[24:25], s[34:35], 13
	s_mul_hi_i32 s1, s12, 0x3800
	s_add_u32 s0, s0, 0xe801e80
	v_writelane_b32 v254, s0, 8
	s_addc_u32 s0, s1, 0
	v_writelane_b32 v254, s0, 9
	s_add_i32 s0, s21, 0
	s_add_i32 s0, s0, 0x21080
	v_writelane_b32 v254, s0, 10
	s_ashr_i32 s1, s56, 31
	s_mov_b32 s0, s56
	s_lshl_b64 s[0:1], s[0:1], 9
	v_writelane_b32 v254, s0, 11
	s_add_i32 s12, s47, 0xfffffe00
	s_nop 0
	v_writelane_b32 v254, s1, 12
	s_lshl_b32 s0, s29, 8
	s_add_i32 s0, s0, s4
	v_writelane_b32 v254, s0, 13
	v_writelane_b32 v254, s12, 14
	s_add_i32 s12, s58, s78
	s_lshl_b64 s[0:1], s[16:17], 2
	v_writelane_b32 v254, s12, 15
	s_lshl_b32 s12, s46, 8
	v_writelane_b32 v254, s12, 16
	s_add_u32 s12, s0, 0x3fa00004
	v_writelane_b32 v254, s12, 17
	v_writelane_b32 v254, s0, 18
	s_nop 1
	v_writelane_b32 v254, s1, 19
	s_addc_u32 s0, s1, 0
	s_lshl_b64 s[14:15], s[14:15], 1
	v_writelane_b32 v254, s0, 20
	s_add_u32 s0, s40, s14
	v_writelane_b32 v254, s14, 21
	s_addc_u32 s1, s41, s15
	s_add_u32 s0, s0, 0x36804800
	v_writelane_b32 v254, s15, 22
	v_writelane_b32 v254, s0, 23
	s_addc_u32 s0, s1, 0
	v_writelane_b32 v254, s0, 24
	s_lshl_b64 s[0:1], s[38:39], 1
	s_add_u32 s0, s10, s0
	s_addc_u32 s1, s11, s1
	s_add_u32 s0, s0, 0x3e200000
	v_writelane_b32 v254, s0, 25
	s_addc_u32 s0, s1, 0
	v_writelane_b32 v254, s0, 26
	s_mov_b32 s0, s36
	v_writelane_b32 v254, s0, 27
	s_nop 1
	v_writelane_b32 v254, s1, 28
	s_lshl_b64 s[0:1], s[36:37], 1
	s_add_u32 s14, s40, s0
	v_writelane_b32 v254, s40, 29
	s_addc_u32 s15, s41, s1
	s_add_u32 s0, s14, 0x2d800800
	v_writelane_b32 v254, s41, 30
	v_writelane_b32 v254, s38, 31
	s_mov_b32 s12, s38
	s_nop 0
	v_writelane_b32 v254, s39, 32
	v_writelane_b32 v254, s0, 33
	s_addc_u32 s0, s15, 0
	v_writelane_b32 v254, s0, 34
	s_lshl_b64 s[0:1], s[12:13], 1
	s_add_u32 s0, s10, s0
	s_mul_hi_i32 s10, s20, 0x300000
	s_addc_u32 s1, s11, s1
	v_writelane_b32 v254, s10, 35
	s_mul_i32 s10, s20, 0x300000
	v_writelane_b32 v254, s10, 36
	s_add_u32 s0, s0, 0x3e200400
	v_writelane_b32 v254, s0, 37
	s_addc_u32 s0, s1, 0
	v_writelane_b32 v254, s0, 38
	s_add_u32 s0, s14, 0x30800800
	v_writelane_b32 v254, s0, 39
	s_addc_u32 s0, s15, 0
	v_writelane_b32 v254, s0, 40
	s_add_u32 s0, s14, 0x2a800800
	v_writelane_b32 v254, s0, 41
	s_addc_u32 s0, s15, 0
	v_writelane_b32 v254, s0, 42
	s_add_i32 s0, s4, 0x550
	v_writelane_b32 v254, s0, 43
	s_add_u32 s0, s52, s22
	v_writelane_b32 v254, s22, 44
	s_addc_u32 s1, s53, s23
	s_nop 0
	v_writelane_b32 v254, s23, 45
	v_writelane_b32 v254, s0, 46
	s_nop 1
	v_writelane_b32 v254, s1, 47
	s_lshl_b64 s[0:1], s[2:3], 1
	v_writelane_b32 v254, s0, 48
	s_nop 1
	v_writelane_b32 v254, s1, 49
	s_lshl_b64 s[0:1], s[4:5], 1
	v_writelane_b32 v254, s0, 50
	s_nop 1
	v_writelane_b32 v254, s1, 51
	s_xor_b64 s[0:1], s[6:7], -1
	v_writelane_b32 v254, s0, 52
	s_nop 1
	v_writelane_b32 v254, s1, 53
	s_lshl_b64 s[0:1], s[8:9], 1
	v_writelane_b32 v254, s0, 54
	s_nop 1
	v_writelane_b32 v254, s1, 55
	s_mul_i32 s0, s56, 6
	v_writelane_b32 v254, s0, 56
	s_mul_hi_i32 s0, s56, 0x600
	v_writelane_b32 v254, s0, 57
	s_mul_i32 s0, s56, 0x600
	v_writelane_b32 v254, s0, 58
	s_add_i32 s0, 0, 0x20160
	v_writelane_b32 v254, s0, 59
	s_add_i32 s0, 0, 0x20164
	v_writelane_b32 v254, s0, 60
	s_add_i32 s0, 0, 0x20400
	v_writelane_b32 v254, s0, 61
	s_add_i32 s0, 0, 0x20180
	v_writelane_b32 v254, s0, 62
	v_writelane_b32 v254, s42, 63
	s_mov_b32 s0, s56
	s_nop 0
	v_writelane_b32 v251, s43, 0
	v_writelane_b32 v251, s44, 1
	s_nop 1
	v_writelane_b32 v251, s45, 2
	v_writelane_b32 v251, s46, 3
	v_writelane_b32 v251, s48, 4
	s_nop 1
	v_writelane_b32 v251, s49, 5
	v_writelane_b32 v251, s47, 6
	v_writelane_b32 v251, s50, 7
	v_writelane_b32 v251, s51, 8
	v_writelane_b32 v251, s60, 9
	v_writelane_b32 v251, s61, 10
	v_writelane_b32 v251, s62, 11
	v_writelane_b32 v251, s63, 12
	v_writelane_b32 v251, s64, 13
	v_writelane_b32 v251, s65, 14
	v_writelane_b32 v251, s66, 15
	v_writelane_b32 v251, s67, 16
	v_writelane_b32 v251, s68, 17
	s_nop 1
	v_writelane_b32 v251, s69, 18
	v_writelane_b32 v251, s70, 19
	s_nop 1
	v_writelane_b32 v251, s71, 20
	v_writelane_b32 v251, s72, 21
	v_writelane_b32 v251, s58, 22
	v_writelane_b32 v251, s78, 23
	v_writelane_b32 v251, s34, 24
	s_nop 1
	v_writelane_b32 v251, s35, 25
	v_writelane_b32 v251, s33, 26
	v_writelane_b32 v251, s18, 27
	s_nop 1
	v_writelane_b32 v251, s19, 28
	v_writelane_b32 v251, s24, 29
	s_nop 1
	v_writelane_b32 v251, s25, 30
	s_branch .LBB0_13

.LBB0_195:
	v_lshl_or_b32 v140, s28, 8, v144
	v_lshl_add_u32 v148, s29, 8, v142
	s_movk_i32 s7, 0x3800
	v_lshlrev_b32_e32 v140, 1, v140
	v_mad_u32_u24 v146, v148, s7, v140
	v_cvt_pk_bf16_f32 v124, v124, v125
	v_cvt_pk_bf16_f32 v125, v126, v127
	v_cvt_pk_bf16_f32 v126, v120, v121
	v_cvt_pk_bf16_f32 v127, v122, v123
	global_store_dwordx4 v146, v[124:127], s[68:69]
	v_cvt_pk_bf16_f32 v112, v112, v113
	v_cvt_pk_bf16_f32 v113, v114, v115
	v_cvt_pk_bf16_f32 v114, v104, v105
	v_cvt_pk_bf16_f32 v115, v106, v107
	global_store_dwordx4 v146, v[112:115], s[68:69] offset:256
	s_andn2_b64 vcc, exec, s[0:1]
	s_mov_b64 s[0:1], -1
	v_cvt_pk_bf16_f32 v104, v116, v117
	v_cvt_pk_bf16_f32 v105, v118, v119
	v_cvt_pk_bf16_f32 v106, v108, v109
	v_cvt_pk_bf16_f32 v107, v110, v111
	v_add_u32_e32 v147, 0x38000, v146
	global_store_dwordx4 v147, v[104:107], s[68:69]
	v_cvt_pk_bf16_f32 v96, v96, v97
	v_cvt_pk_bf16_f32 v97, v98, v99
	v_cvt_pk_bf16_f32 v98, v88, v89
	v_cvt_pk_bf16_f32 v99, v90, v91
	global_store_dwordx4 v147, v[96:99], s[68:69] offset:256
	v_cvt_pk_bf16_f32 v88, v100, v101
	v_cvt_pk_bf16_f32 v89, v102, v103
	v_cvt_pk_bf16_f32 v90, v92, v93
	v_cvt_pk_bf16_f32 v91, v94, v95
	v_add_u32_e32 v149, 0x70000, v146
	global_store_dwordx4 v149, v[88:91], s[68:69]
	v_cvt_pk_bf16_f32 v80, v80, v81
	v_cvt_pk_bf16_f32 v81, v82, v83
	v_cvt_pk_bf16_f32 v82, v72, v73
	v_cvt_pk_bf16_f32 v83, v74, v75
	global_store_dwordx4 v149, v[80:83], s[68:69] offset:256
	v_cvt_pk_bf16_f32 v72, v84, v85
	v_cvt_pk_bf16_f32 v73, v86, v87
	v_cvt_pk_bf16_f32 v74, v76, v77
	v_cvt_pk_bf16_f32 v75, v78, v79
	v_add_u32_e32 v147, 0xa8000, v146
	global_store_dwordx4 v147, v[72:75], s[68:69]
	v_cvt_pk_bf16_f32 v68, v68, v69
	v_cvt_pk_bf16_f32 v69, v70, v71
	v_cvt_pk_bf16_f32 v70, v64, v65
	v_cvt_pk_bf16_f32 v71, v66, v67
	global_store_dwordx4 v147, v[68:71], s[68:69] offset:256
	v_cvt_pk_bf16_f32 v60, v60, v61
	v_cvt_pk_bf16_f32 v61, v62, v63
	v_cvt_pk_bf16_f32 v62, v56, v57
	v_cvt_pk_bf16_f32 v63, v58, v59
	v_add_u32_e32 v149, 0x1c0000, v146
	global_store_dwordx4 v149, v[60:63], s[68:69]
	v_cvt_pk_bf16_f32 v48, v48, v49
	v_cvt_pk_bf16_f32 v49, v50, v51
	v_cvt_pk_bf16_f32 v50, v40, v41
	v_cvt_pk_bf16_f32 v51, v42, v43
	global_store_dwordx4 v149, v[48:51], s[68:69] offset:256
	v_cvt_pk_bf16_f32 v40, v52, v53
	v_cvt_pk_bf16_f32 v41, v54, v55
	v_cvt_pk_bf16_f32 v42, v44, v45
	v_cvt_pk_bf16_f32 v43, v46, v47
	v_add_u32_e32 v147, 0x1f8000, v146
	global_store_dwordx4 v147, v[40:43], s[68:69]
	v_cvt_pk_bf16_f32 v32, v32, v33
	v_cvt_pk_bf16_f32 v33, v34, v35
	v_cvt_pk_bf16_f32 v34, v24, v25
	v_cvt_pk_bf16_f32 v35, v26, v27
	global_store_dwordx4 v147, v[32:35], s[68:69] offset:256
	v_cvt_pk_bf16_f32 v24, v36, v37
	v_cvt_pk_bf16_f32 v25, v38, v39
	v_cvt_pk_bf16_f32 v26, v28, v29
	v_cvt_pk_bf16_f32 v27, v30, v31
	v_add_u32_e32 v149, 0x230000, v146
	global_store_dwordx4 v149, v[24:27], s[68:69]
	v_cvt_pk_bf16_f32 v16, v16, v17
	v_cvt_pk_bf16_f32 v17, v18, v19
	v_cvt_pk_bf16_f32 v18, v8, v9
	v_cvt_pk_bf16_f32 v19, v10, v11
	global_store_dwordx4 v149, v[16:19], s[68:69] offset:256
	v_cvt_pk_bf16_f32 v8, v20, v21
	v_cvt_pk_bf16_f32 v9, v22, v23
	v_cvt_pk_bf16_f32 v10, v12, v13
	v_cvt_pk_bf16_f32 v11, v14, v15
	v_add_u32_e32 v147, 0x268000, v146
	global_store_dwordx4 v147, v[8:11], s[68:69]
	v_cvt_pk_bf16_f32 v4, v4, v5
	v_cvt_pk_bf16_f32 v5, v6, v7
	v_cvt_pk_bf16_f32 v6, v0, v1
	v_cvt_pk_bf16_f32 v7, v2, v3
	global_store_dwordx4 v147, v[4:7], s[68:69] offset:256
	s_cbranch_vccnz .LBB0_188
	s_andn2_b64 vcc, exec, s[2:3]
	s_cbranch_vccnz .LBB0_187
	s_barrier
	s_branch .LBB0_187

.LBB0_1513:
	s_andn2_b64 vcc, exec, s[0:1]
	s_mov_b32 s98, 0xbfb8aa3b
	s_mov_b32 s99, 0xbfb8aa3b
	s_mov_b32 s100, 1.0
	s_mov_b32 s101, 1.0
	s_movk_i32 s7, 0x2c00
	v_lshl_or_b32 v146, s28, 7, v142
	v_lshl_add_u32 v144, s29, 8, v140
	v_lshlrev_b32_e32 v146, 1, v146
	v_mad_u32_u24 v148, v144, s7, v146
	v_pk_mul_f32 v[162:163], v[124:125], s[98:99]
	v_pk_mul_f32 v[164:165], v[126:127], s[98:99]
	v_pk_mul_f32 v[166:167], v[116:117], s[98:99]
	v_pk_mul_f32 v[168:169], v[118:119], s[98:99]
	v_exp_f32_e32 v162, v162
	v_exp_f32_e32 v163, v163
	v_exp_f32_e32 v164, v164
	v_exp_f32_e32 v165, v165
	v_exp_f32_e32 v166, v166
	v_exp_f32_e32 v167, v167
	v_exp_f32_e32 v168, v168
	v_exp_f32_e32 v169, v169
	v_pk_add_f32 v[162:163], v[162:163], s[100:101]
	v_pk_add_f32 v[164:165], v[164:165], s[100:101]
	v_pk_add_f32 v[166:167], v[166:167], s[100:101]
	v_pk_add_f32 v[168:169], v[168:169], s[100:101]
	v_rcp_f32_e32 v162, v162
	v_rcp_f32_e32 v163, v163
	v_rcp_f32_e32 v164, v164
	v_rcp_f32_e32 v165, v165
	v_rcp_f32_e32 v166, v166
	v_rcp_f32_e32 v167, v167
	v_rcp_f32_e32 v168, v168
	v_rcp_f32_e32 v169, v169
	v_pk_mul_f32 v[162:163], v[124:125], v[162:163]
	v_pk_mul_f32 v[164:165], v[126:127], v[164:165]
	v_pk_mul_f32 v[166:167], v[116:117], v[166:167]
	v_pk_mul_f32 v[168:169], v[118:119], v[168:169]
	v_pk_mul_f32 v[162:163], v[162:163], v[120:121]
	v_pk_mul_f32 v[164:165], v[164:165], v[122:123]
	v_pk_mul_f32 v[166:167], v[166:167], v[112:113]
	v_pk_mul_f32 v[168:169], v[168:169], v[114:115]
	v_cvt_pk_bf16_f32 v124, v162, v163
	v_cvt_pk_bf16_f32 v125, v164, v165
	v_cvt_pk_bf16_f32 v126, v166, v167
	v_cvt_pk_bf16_f32 v127, v168, v169
	global_store_dwordx4 v148, v[124:127], s[68:69]
	v_pk_mul_f32 v[170:171], v[108:109], s[98:99]
	v_pk_mul_f32 v[172:173], v[110:111], s[98:99]
	v_pk_mul_f32 v[174:175], v[100:101], s[98:99]
	v_pk_mul_f32 v[176:177], v[102:103], s[98:99]
	v_exp_f32_e32 v170, v170
	v_exp_f32_e32 v171, v171
	v_exp_f32_e32 v172, v172
	v_exp_f32_e32 v173, v173
	v_exp_f32_e32 v174, v174
	v_exp_f32_e32 v175, v175
	v_exp_f32_e32 v176, v176
	v_exp_f32_e32 v177, v177
	v_pk_add_f32 v[170:171], v[170:171], s[100:101]
	v_pk_add_f32 v[172:173], v[172:173], s[100:101]
	v_pk_add_f32 v[174:175], v[174:175], s[100:101]
	v_pk_add_f32 v[176:177], v[176:177], s[100:101]
	v_rcp_f32_e32 v170, v170
	v_rcp_f32_e32 v171, v171
	v_rcp_f32_e32 v172, v172
	v_rcp_f32_e32 v173, v173
	v_rcp_f32_e32 v174, v174
	v_rcp_f32_e32 v175, v175
	v_rcp_f32_e32 v176, v176
	v_rcp_f32_e32 v177, v177
	v_pk_mul_f32 v[170:171], v[108:109], v[170:171]
	v_pk_mul_f32 v[172:173], v[110:111], v[172:173]
	v_pk_mul_f32 v[174:175], v[100:101], v[174:175]
	v_pk_mul_f32 v[176:177], v[102:103], v[176:177]
	v_pk_mul_f32 v[170:171], v[170:171], v[104:105]
	v_pk_mul_f32 v[172:173], v[172:173], v[106:107]
	v_pk_mul_f32 v[174:175], v[174:175], v[96:97]
	v_pk_mul_f32 v[176:177], v[176:177], v[98:99]
	v_cvt_pk_bf16_f32 v108, v170, v171
	v_cvt_pk_bf16_f32 v109, v172, v173
	v_cvt_pk_bf16_f32 v110, v174, v175
	v_cvt_pk_bf16_f32 v111, v176, v177
	v_add_u32_e32 v149, 0x2c000, v148
	global_store_dwordx4 v149, v[108:111], s[68:69]
	v_pk_mul_f32 v[162:163], v[92:93], s[98:99]
	v_pk_mul_f32 v[164:165], v[94:95], s[98:99]
	v_pk_mul_f32 v[166:167], v[84:85], s[98:99]
	v_pk_mul_f32 v[168:169], v[86:87], s[98:99]
	v_exp_f32_e32 v162, v162
	v_exp_f32_e32 v163, v163
	v_exp_f32_e32 v164, v164
	v_exp_f32_e32 v165, v165
	v_exp_f32_e32 v166, v166
	v_exp_f32_e32 v167, v167
	v_exp_f32_e32 v168, v168
	v_exp_f32_e32 v169, v169
	v_pk_add_f32 v[162:163], v[162:163], s[100:101]
	v_pk_add_f32 v[164:165], v[164:165], s[100:101]
	v_pk_add_f32 v[166:167], v[166:167], s[100:101]
	v_pk_add_f32 v[168:169], v[168:169], s[100:101]
	v_rcp_f32_e32 v162, v162
	v_rcp_f32_e32 v163, v163
	v_rcp_f32_e32 v164, v164
	v_rcp_f32_e32 v165, v165
	v_rcp_f32_e32 v166, v166
	v_rcp_f32_e32 v167, v167
	v_rcp_f32_e32 v168, v168
	v_rcp_f32_e32 v169, v169
	v_pk_mul_f32 v[162:163], v[92:93], v[162:163]
	v_pk_mul_f32 v[164:165], v[94:95], v[164:165]
	v_pk_mul_f32 v[166:167], v[84:85], v[166:167]
	v_pk_mul_f32 v[168:169], v[86:87], v[168:169]
	v_pk_mul_f32 v[162:163], v[162:163], v[88:89]
	v_pk_mul_f32 v[164:165], v[164:165], v[90:91]
	v_pk_mul_f32 v[166:167], v[166:167], v[80:81]
	v_pk_mul_f32 v[168:169], v[168:169], v[82:83]
	v_cvt_pk_bf16_f32 v92, v162, v163
	v_cvt_pk_bf16_f32 v93, v164, v165
	v_cvt_pk_bf16_f32 v94, v166, v167
	v_cvt_pk_bf16_f32 v95, v168, v169
	v_add_u32_e32 v147, 0x58000, v148
	global_store_dwordx4 v147, v[92:95], s[68:69]
	v_pk_mul_f32 v[170:171], v[76:77], s[98:99]
	v_pk_mul_f32 v[172:173], v[78:79], s[98:99]
	v_pk_mul_f32 v[174:175], v[68:69], s[98:99]
	v_pk_mul_f32 v[176:177], v[70:71], s[98:99]
	v_exp_f32_e32 v170, v170
	v_exp_f32_e32 v171, v171
	v_exp_f32_e32 v172, v172
	v_exp_f32_e32 v173, v173
	v_exp_f32_e32 v174, v174
	v_exp_f32_e32 v175, v175
	v_exp_f32_e32 v176, v176
	v_exp_f32_e32 v177, v177
	v_pk_add_f32 v[170:171], v[170:171], s[100:101]
	v_pk_add_f32 v[172:173], v[172:173], s[100:101]
	v_pk_add_f32 v[174:175], v[174:175], s[100:101]
	v_pk_add_f32 v[176:177], v[176:177], s[100:101]
	v_rcp_f32_e32 v170, v170
	v_rcp_f32_e32 v171, v171
	v_rcp_f32_e32 v172, v172
	v_rcp_f32_e32 v173, v173
	v_rcp_f32_e32 v174, v174
	v_rcp_f32_e32 v175, v175
	v_rcp_f32_e32 v176, v176
	v_rcp_f32_e32 v177, v177
	v_pk_mul_f32 v[170:171], v[76:77], v[170:171]
	v_pk_mul_f32 v[172:173], v[78:79], v[172:173]
	v_pk_mul_f32 v[174:175], v[68:69], v[174:175]
	v_pk_mul_f32 v[176:177], v[70:71], v[176:177]
	v_pk_mul_f32 v[170:171], v[170:171], v[72:73]
	v_pk_mul_f32 v[172:173], v[172:173], v[74:75]
	v_pk_mul_f32 v[174:175], v[174:175], v[64:65]
	v_pk_mul_f32 v[176:177], v[176:177], v[66:67]
	v_cvt_pk_bf16_f32 v76, v170, v171
	v_cvt_pk_bf16_f32 v77, v172, v173
	v_cvt_pk_bf16_f32 v78, v174, v175
	v_cvt_pk_bf16_f32 v79, v176, v177
	v_add_u32_e32 v149, 0x84000, v148
	global_store_dwordx4 v149, v[76:79], s[68:69]
	v_pk_mul_f32 v[162:163], v[60:61], s[98:99]
	v_pk_mul_f32 v[164:165], v[62:63], s[98:99]
	v_pk_mul_f32 v[166:167], v[52:53], s[98:99]
	v_pk_mul_f32 v[168:169], v[54:55], s[98:99]
	v_exp_f32_e32 v162, v162
	v_exp_f32_e32 v163, v163
	v_exp_f32_e32 v164, v164
	v_exp_f32_e32 v165, v165
	v_exp_f32_e32 v166, v166
	v_exp_f32_e32 v167, v167
	v_exp_f32_e32 v168, v168
	v_exp_f32_e32 v169, v169
	v_pk_add_f32 v[162:163], v[162:163], s[100:101]
	v_pk_add_f32 v[164:165], v[164:165], s[100:101]
	v_pk_add_f32 v[166:167], v[166:167], s[100:101]
	v_pk_add_f32 v[168:169], v[168:169], s[100:101]
	v_rcp_f32_e32 v162, v162
	v_rcp_f32_e32 v163, v163
	v_rcp_f32_e32 v164, v164
	v_rcp_f32_e32 v165, v165
	v_rcp_f32_e32 v166, v166
	v_rcp_f32_e32 v167, v167
	v_rcp_f32_e32 v168, v168
	v_rcp_f32_e32 v169, v169
	v_pk_mul_f32 v[162:163], v[60:61], v[162:163]
	v_pk_mul_f32 v[164:165], v[62:63], v[164:165]
	v_pk_mul_f32 v[166:167], v[52:53], v[166:167]
	v_pk_mul_f32 v[168:169], v[54:55], v[168:169]
	v_pk_mul_f32 v[162:163], v[162:163], v[56:57]
	v_pk_mul_f32 v[164:165], v[164:165], v[58:59]
	v_pk_mul_f32 v[166:167], v[166:167], v[48:49]
	v_pk_mul_f32 v[168:169], v[168:169], v[50:51]
	v_cvt_pk_bf16_f32 v60, v162, v163
	v_cvt_pk_bf16_f32 v61, v164, v165
	v_cvt_pk_bf16_f32 v62, v166, v167
	v_cvt_pk_bf16_f32 v63, v168, v169
	v_add_u32_e32 v147, 0x160000, v148
	global_store_dwordx4 v147, v[60:63], s[68:69]
	v_pk_mul_f32 v[170:171], v[44:45], s[98:99]
	v_pk_mul_f32 v[172:173], v[46:47], s[98:99]
	v_pk_mul_f32 v[174:175], v[36:37], s[98:99]
	v_pk_mul_f32 v[176:177], v[38:39], s[98:99]
	v_exp_f32_e32 v170, v170
	v_exp_f32_e32 v171, v171
	v_exp_f32_e32 v172, v172
	v_exp_f32_e32 v173, v173
	v_exp_f32_e32 v174, v174
	v_exp_f32_e32 v175, v175
	v_exp_f32_e32 v176, v176
	v_exp_f32_e32 v177, v177
	v_pk_add_f32 v[170:171], v[170:171], s[100:101]
	v_pk_add_f32 v[172:173], v[172:173], s[100:101]
	v_pk_add_f32 v[174:175], v[174:175], s[100:101]
	v_pk_add_f32 v[176:177], v[176:177], s[100:101]
	v_rcp_f32_e32 v170, v170
	v_rcp_f32_e32 v171, v171
	v_rcp_f32_e32 v172, v172
	v_rcp_f32_e32 v173, v173
	v_rcp_f32_e32 v174, v174
	v_rcp_f32_e32 v175, v175
	v_rcp_f32_e32 v176, v176
	v_rcp_f32_e32 v177, v177
	v_pk_mul_f32 v[170:171], v[44:45], v[170:171]
	v_pk_mul_f32 v[172:173], v[46:47], v[172:173]
	v_pk_mul_f32 v[174:175], v[36:37], v[174:175]
	v_pk_mul_f32 v[176:177], v[38:39], v[176:177]
	v_pk_mul_f32 v[170:171], v[170:171], v[40:41]
	v_pk_mul_f32 v[172:173], v[172:173], v[42:43]
	v_pk_mul_f32 v[174:175], v[174:175], v[32:33]
	v_pk_mul_f32 v[176:177], v[176:177], v[34:35]
	v_cvt_pk_bf16_f32 v44, v170, v171
	v_cvt_pk_bf16_f32 v45, v172, v173
	v_cvt_pk_bf16_f32 v46, v174, v175
	v_cvt_pk_bf16_f32 v47, v176, v177
	v_add_u32_e32 v149, 0x18c000, v148
	global_store_dwordx4 v149, v[44:47], s[68:69]
	v_pk_mul_f32 v[162:163], v[28:29], s[98:99]
	v_pk_mul_f32 v[164:165], v[30:31], s[98:99]
	v_pk_mul_f32 v[166:167], v[20:21], s[98:99]
	v_pk_mul_f32 v[168:169], v[22:23], s[98:99]
	v_exp_f32_e32 v162, v162
	v_exp_f32_e32 v163, v163
	v_exp_f32_e32 v164, v164
	v_exp_f32_e32 v165, v165
	v_exp_f32_e32 v166, v166
	v_exp_f32_e32 v167, v167
	v_exp_f32_e32 v168, v168
	v_exp_f32_e32 v169, v169
	v_pk_add_f32 v[162:163], v[162:163], s[100:101]
	v_pk_add_f32 v[164:165], v[164:165], s[100:101]
	v_pk_add_f32 v[166:167], v[166:167], s[100:101]
	v_pk_add_f32 v[168:169], v[168:169], s[100:101]
	v_rcp_f32_e32 v162, v162
	v_rcp_f32_e32 v163, v163
	v_rcp_f32_e32 v164, v164
	v_rcp_f32_e32 v165, v165
	v_rcp_f32_e32 v166, v166
	v_rcp_f32_e32 v167, v167
	v_rcp_f32_e32 v168, v168
	v_rcp_f32_e32 v169, v169
	v_pk_mul_f32 v[162:163], v[28:29], v[162:163]
	v_pk_mul_f32 v[164:165], v[30:31], v[164:165]
	v_pk_mul_f32 v[166:167], v[20:21], v[166:167]
	v_pk_mul_f32 v[168:169], v[22:23], v[168:169]
	v_pk_mul_f32 v[162:163], v[162:163], v[24:25]
	v_pk_mul_f32 v[164:165], v[164:165], v[26:27]
	v_pk_mul_f32 v[166:167], v[166:167], v[16:17]
	v_pk_mul_f32 v[168:169], v[168:169], v[18:19]
	v_cvt_pk_bf16_f32 v28, v162, v163
	v_cvt_pk_bf16_f32 v29, v164, v165
	v_cvt_pk_bf16_f32 v30, v166, v167
	v_cvt_pk_bf16_f32 v31, v168, v169
	v_add_u32_e32 v147, 0x1b8000, v148
	global_store_dwordx4 v147, v[28:31], s[68:69]
	v_pk_mul_f32 v[170:171], v[12:13], s[98:99]
	v_pk_mul_f32 v[172:173], v[14:15], s[98:99]
	v_pk_mul_f32 v[174:175], v[4:5], s[98:99]
	v_pk_mul_f32 v[176:177], v[6:7], s[98:99]
	v_exp_f32_e32 v170, v170
	v_exp_f32_e32 v171, v171
	v_exp_f32_e32 v172, v172
	v_exp_f32_e32 v173, v173
	v_exp_f32_e32 v174, v174
	v_exp_f32_e32 v175, v175
	v_exp_f32_e32 v176, v176
	v_exp_f32_e32 v177, v177
	v_pk_add_f32 v[170:171], v[170:171], s[100:101]
	v_pk_add_f32 v[172:173], v[172:173], s[100:101]
	v_pk_add_f32 v[174:175], v[174:175], s[100:101]
	v_pk_add_f32 v[176:177], v[176:177], s[100:101]
	v_rcp_f32_e32 v170, v170
	v_rcp_f32_e32 v171, v171
	v_rcp_f32_e32 v172, v172
	v_rcp_f32_e32 v173, v173
	v_rcp_f32_e32 v174, v174
	v_rcp_f32_e32 v175, v175
	v_rcp_f32_e32 v176, v176
	v_rcp_f32_e32 v177, v177
	v_pk_mul_f32 v[170:171], v[12:13], v[170:171]
	v_pk_mul_f32 v[172:173], v[14:15], v[172:173]
	v_pk_mul_f32 v[174:175], v[4:5], v[174:175]
	v_pk_mul_f32 v[176:177], v[6:7], v[176:177]
	v_pk_mul_f32 v[170:171], v[170:171], v[8:9]
	v_pk_mul_f32 v[172:173], v[172:173], v[10:11]
	v_pk_mul_f32 v[174:175], v[174:175], v[0:1]
	v_pk_mul_f32 v[176:177], v[176:177], v[2:3]
	v_cvt_pk_bf16_f32 v12, v170, v171
	v_cvt_pk_bf16_f32 v13, v172, v173
	v_cvt_pk_bf16_f32 v14, v174, v175
	v_cvt_pk_bf16_f32 v15, v176, v177
	v_add_u32_e32 v149, 0x1e4000, v148
	global_store_dwordx4 v149, v[12:15], s[68:69]
	s_mov_b64 s[14:15], -1
	s_cbranch_vccnz .LBB0_1506
	s_andn2_b64 vcc, exec, s[2:3]
	s_cbranch_vccnz .LBB0_1505
	s_barrier
	s_branch .LBB0_1505

.LBB0_1576:
	v_bfe_u32 v18, v8, 4, 2
	v_readlane_b32 s12, v253, 58
	v_and_b32_e32 v9, 15, v8
	v_lshlrev_b32_e32 v19, 4, v18
	v_lshlrev_b32_e32 v8, 2, v8
	s_lshl_b32 s1, s1, 5
	v_readlane_b32 s13, v253, 59
	v_lshl_or_b32 v140, s2, 6, v9
	v_lshl_or_b32 v9, v9, 6, v19
	s_lshl_b32 s2, s2, 13
	v_and_b32_e32 v8, 32, v8
	s_and_b32 s1, s1, 0x60
	v_lshl_add_u64 v[10:11], s[12:13], 0, v[152:153]
	v_mov_b32_e32 v129, v153
	v_readlane_b32 s10, v253, 54
	v_bitop3_b32 v19, v9, s2, v8 bitop3:0xde
	s_lshl_b32 s2, s1, 7
	v_lshl_add_u64 v[12:13], s[12:13], 0, v[128:129]
	v_readlane_b32 s11, v253, 55
	v_bitop3_b32 v141, v9, s2, v8 bitop3:0xde
	s_add_i32 m0, s19, 0x18000
	v_lshl_add_u64 v[8:9], v[10:11], 0, s[6:7]
	v_lshl_add_u64 v[14:15], s[10:11], 0, v[152:153]
	s_waitcnt vmcnt(2)
	s_barrier
	global_load_lds_dwordx4 v[8:9], off
	v_lshl_add_u64 v[8:9], v[12:13], 0, s[6:7]
	s_add_i32 m0, s19, 0x1a000
	s_add_i32 s23, s19, 0x8000
	v_lshl_add_u64 v[16:17], s[10:11], 0, v[128:129]
	global_load_lds_dwordx4 v[8:9], off
	v_lshl_add_u64 v[8:9], v[14:15], 0, s[6:7]
	s_mov_b32 m0, s23
	s_add_i32 s24, s19, 0xa000
	v_readlane_b32 s2, v253, 60
	global_load_lds_dwordx4 v[8:9], off
	v_lshl_add_u64 v[8:9], v[16:17], 0, s[6:7]
	s_mov_b32 m0, s24
	v_readlane_b32 s3, v253, 61
	global_load_lds_dwordx4 v[8:9], off
	s_add_i32 m0, s19, 0x1c000
	v_lshl_add_u64 v[8:9], s[2:3], 0, v[152:153]
	global_load_lds_dwordx4 v[8:9], off
	v_lshl_add_u64 v[8:9], s[2:3], 0, v[128:129]
	s_add_i32 m0, s19, 0x1e000
	s_movk_i32 s2, 0x1600
	global_load_lds_dwordx4 v[8:9], off
	v_lshrrev_b32_e32 v8, 1, v0
	v_mul_lo_u32 v0, v1, s2
	s_mov_b32 s3, 0x16000
	s_cmpk_lt_u32 s0, 0x100
	v_lshl_or_b32 v142, v18, 2, s1
	v_mad_u64_u32 v[0:1], s[0:1], v8, s3, v[0:1]
	v_or_b32_e32 v0, v0, v2
	v_add_lshl_u32 v0, v0, v3, 1
	v_mov_b32_e32 v1, v153
	s_mov_b64 s[8:9], 0x160080
	v_lshl_add_u64 v[130:131], v[0:1], 0, s[8:9]
	v_lshrrev_b32_e32 v1, 1, v5
	v_mul_lo_u32 v0, v4, s2
	v_mad_u64_u32 v[0:1], s[0:1], v1, s3, v[0:1]
	s_waitcnt vmcnt(6)
	v_or_b32_e32 v0, v0, v6
	v_add_lshl_u32 v0, v0, v7, 1
	v_mov_b32_e32 v1, v153
	v_readlane_b32 s0, v253, 52
	s_cselect_b64 s[6:7], -1, 0
	v_lshl_add_u64 v[132:133], v[0:1], 0, s[8:9]
	s_mov_b32 s25, 0
	v_add_u32_e32 v143, 0, v19
	v_readlane_b32 s28, v253, 49
	s_xor_b32 s29, s0, 12
	s_barrier
	v_readlane_b32 s1, v253, 53
	s_branch .LBB0_1579

.LBB0_1584:
	s_ashr_i32 s0, s8, 3
	s_add_i32 s0, s14, s0
	s_ashr_i32 s1, s0, 31
	s_lshr_b32 s1, s1, 27
	s_add_i32 s1, s0, s1
	s_ashr_i32 s8, s1, 5
	s_lshl_b32 s8, s8, 2
	s_sub_i32 s9, 0x80, s8
	s_min_i32 s9, s9, 4
	s_abs_i32 s14, s9
	v_cvt_f32_u32_e32 v0, s14
	s_sub_i32 s16, 0, s14
	s_andn2_b32 s1, s1, 31
	s_sub_i32 s0, s0, s1
	v_rcp_iflag_f32_e32 v0, v0
	s_abs_i32 s1, s0
	s_xor_b32 s15, s0, s9
	s_ashr_i32 s15, s15, 31
	v_mul_f32_e32 v0, 0x4f7ffffe, v0
	v_cvt_u32_f32_e32 v0, v0
	s_nop 0
	v_readfirstlane_b32 s17, v0
	s_mul_i32 s16, s16, s17
	s_mul_hi_u32 s16, s17, s16
	s_add_i32 s17, s17, s16
	s_mul_hi_u32 s16, s1, s17
	s_mul_i32 s17, s16, s14
	s_sub_i32 s1, s1, s17
	s_add_i32 s26, s16, 1
	s_sub_i32 s17, s1, s14
	s_cmp_ge_u32 s1, s14
	s_cselect_b32 s16, s26, s16
	s_cselect_b32 s1, s17, s1
	s_add_i32 s17, s16, 1
	s_cmp_ge_u32 s1, s14
	s_cselect_b32 s1, s17, s16
	s_xor_b32 s1, s1, s15
	s_sub_i32 s26, s1, s15
	s_mul_i32 s1, s26, s9
	s_sub_i32 s0, s0, s1
	s_add_i32 s27, s8, s0
	s_xor_b32 s27, s27, 12
